# state-wave loads moved after compute in GLA scan + L2 prefetch of next chunks by wave 4; lr_phase moved after in-proj GEMM; WA touched before P7
# speedup vs baseline: 1.0064x; 1.0064x over previous
.LBB0_479:
	s_or_b64 exec, exec, s[2:3]
	v_lshlrev_b32_e32 v244, 4, v188
	s_mul_i32 s98, s30, 0x30000
	s_add_u32 s100, s70, s98
	s_addc_u32 s101, s71, 0
	s_mov_b32 s99, 24
.Lwarm_wa:
	global_load_dwordx4 v[240:243], v244, s[100:101]
	s_add_u32 s100, s100, 0x2000
	s_addc_u32 s101, s101, 0
	s_sub_u32 s99, s99, 1
	s_cmp_lg_u32 s99, 0
	s_cbranch_scc1 .Lwarm_wa
	s_waitcnt vmcnt(0)
	s_barrier
	s_and_saveexec_b64 s[0:1], s[28:29]
	s_cbranch_execz .LBB0_531
	s_add_i32 s2, 0, 0x24800
	v_mov_b32_e32 v0, s2
	s_waitcnt vmcnt(0) expcnt(0) lgkmcnt(0)
	ds_read_b32 v2, v0
	s_add_i32 s2, 0, 0x24804
	v_mov_b32_e32 v0, s2
	ds_read_b32 v0, v0
	s_waitcnt lgkmcnt(1)
	v_cmp_ne_u32_e32 vcc, 0, v2
	s_cbranch_vccnz .LBB0_495
	v_readlane_b32 s2, v253, 0
	s_mul_i32 s16, s69, s2
	s_add_u32 s2, s50, 0x1000
	s_addc_u32 s3, s51, 0
	s_add_u32 s4, s50, 0x1100
	s_addc_u32 s5, s51, 0
	s_add_u32 s6, s50, 0x1200
	s_addc_u32 s7, s51, 0
	s_add_u32 s8, s50, 0x1300
	s_mul_i32 s16, s16, s68
	s_addc_u32 s9, s51, 0
	s_mov_b32 s17, 1
	v_mov_b32_e32 v16, 0
	s_branch .LBB0_483

.LBB0_531:
	s_or_b64 exec, exec, s[0:1]
	s_waitcnt lgkmcnt(0)
	v_mov_b32_e32 v0, v188
	s_add_u32 s0, s50, 0x100000
	s_barrier
	s_addc_u32 s1, s51, 0
.LBB0_536:
	v_readlane_b32 s2, v253, 1
	v_mov_b32_e32 v9, v188
	v_readlane_b32 s3, v253, 2
	s_andn2_b64 vcc, exec, s[2:3]
	v_readfirstlane_b32 s4, v9
	s_cbranch_vccnz .LBB0_552
	v_lshlrev_b32_e32 v0, 4, v9
	v_add_u32_e32 v1, 0x2000, v0
	v_ashrrev_i32_e32 v2, 31, v1
	v_lshrrev_b32_e32 v2, 22, v2
	v_add_u32_e32 v2, v1, v2
	v_ashrrev_i32_e32 v8, 10, v2
	v_mul_i32_i24_e32 v2, 0x400, v8
	v_sub_u32_e32 v1, v1, v2
	v_lshrrev_b32_e32 v2, 4, v1
	v_bitop3_b32 v1, v2, v1, 32 bitop3:0x6c
	v_ashrrev_i32_e32 v2, 31, v1
	v_lshrrev_b32_e32 v2, 26, v2
	v_add_u32_e32 v2, v1, v2
	v_lshlrev_b32_e32 v3, 3, v8
	v_ashrrev_i32_e32 v10, 6, v2
	v_and_b32_e32 v3, -16, v3
	v_add_u32_e32 v3, v10, v3
	v_lshlrev_b32_e32 v4, 2, v3
	v_and_b32_e32 v5, 3, v10
	s_lshr_b32 s2, s87, 29
	v_and_or_b32 v4, v4, 48, v5
	v_lshlrev_b32_e32 v5, 1, v3
	v_lshrrev_b32_e32 v6, 2, v3
	v_and_b32_e32 v2, 0xc0, v2
	s_add_i32 s2, s30, s2
	s_ashr_i32 s8, s4, 6
	v_and_b32_e32 v5, 0xfffc0, v5
	v_and_b32_e32 v6, 4, v6
	v_sub_u32_e32 v1, v1, v2
	v_mov_b32_e32 v2, 1
	s_ashr_i32 s5, s2, 3
	s_and_b32 s2, s2, -8
	s_ashr_i32 s3, s4, 8
	s_lshl_b32 s35, s8, 10
	v_or3_b32 v4, v4, v5, v6
	v_lshlrev_b32_e32 v5, 5, v8
	v_ashrrev_i16_sdwa v1, v2, sext(v1) dst_sel:DWORD dst_unused:UNUSED_PAD src0_sel:DWORD src1_sel:BYTE_0
	s_sub_i32 s2, s30, s2
	v_and_b32_e32 v5, 32, v5
	v_bfe_i32 v11, v1, 0, 16
	s_cmp_lt_i32 s2, 0
	s_movk_i32 s36, 0x181
	v_add_lshl_u32 v1, v5, v11, 1
	s_cselect_b32 s6, s36, 0x180
	v_lshl_add_u32 v128, v4, 12, v1
	v_lshl_add_u32 v130, v3, 12, v1
	v_bfe_i32 v1, v9, 27, 1
	s_mul_i32 s2, s2, s6
	v_lshrrev_b32_e32 v1, 22, v1
	s_add_i32 s2, s2, s5
	v_add_u32_e32 v1, v0, v1
	s_mul_hi_i32 s5, s2, 0x2aaaaaab
	v_and_b32_e32 v1, 0xfffffc00, v1
	s_lshr_b32 s6, s5, 31
	s_ashr_i32 s5, s5, 6
	v_sub_u32_e32 v0, v0, v1
	s_add_i32 s5, s5, s6
	v_lshrrev_b32_e32 v1, 4, v0
	v_ashrrev_i32_e32 v3, 31, v9
	s_lshl_b32 s6, s5, 3
	s_mulk_i32 s5, 0x180
	v_bitop3_b32 v0, v1, v0, 32 bitop3:0x6c
	v_lshrrev_b32_e32 v3, 26, v3
	s_sub_i32 s5, s2, s5
	v_ashrrev_i32_e32 v1, 31, v0
	v_add_u32_e32 v3, v9, v3
	s_sext_i32_i16 s2, s5
	v_lshrrev_b32_e32 v1, 26, v1
	v_ashrrev_i32_e32 v13, 6, v3
	s_bfe_u32 s2, s2, 0x3001c
	v_add_u32_e32 v1, v0, v1
	v_lshlrev_b32_e32 v3, 3, v13
	s_add_i32 s7, s5, s2
	v_ashrrev_i32_e32 v12, 6, v1
	v_and_b32_e32 v3, -16, v3
	s_sext_i32_i16 s2, s7
	s_and_b32 s7, s7, 0xfff8
	v_add_u32_e32 v3, v12, v3
	s_sub_i32 s5, s5, s7
	v_lshlrev_b32_e32 v4, 2, v3
	v_and_b32_e32 v5, 3, v12
	s_sext_i32_i16 s5, s5
	v_and_or_b32 v4, v4, 48, v5
	v_lshlrev_b32_e32 v5, 1, v3
	v_lshrrev_b32_e32 v6, 2, v3
	v_and_b32_e32 v1, 0xc0, v1
	s_lshr_b32 s2, s2, 3
	s_add_i32 s18, s6, s5
	v_and_b32_e32 v5, 0xfffc0, v5
	v_and_b32_e32 v6, 4, v6
	v_sub_u32_e32 v0, v0, v1
	s_ashr_i32 s19, s18, 31
	s_bfe_i64 s[10:11], s[2:3], 0x100000
	v_or3_b32 v4, v4, v5, v6
	v_lshlrev_b32_e32 v5, 5, v13
	v_ashrrev_i16_sdwa v0, v2, sext(v0) dst_sel:DWORD dst_unused:UNUSED_PAD src0_sel:DWORD src1_sel:BYTE_0
	s_lshl_b64 s[6:7], s[18:19], 20
	s_lshl_b64 s[10:11], s[10:11], 20
	v_and_b32_e32 v5, 32, v5
	v_bfe_i32 v14, v0, 0, 16
	s_add_u32 s24, s70, s10
	v_add_lshl_u32 v0, v5, v14, 1
	s_addc_u32 s25, s71, s11
	s_add_i32 s19, s35, 0
	v_lshl_add_u32 v132, v4, 12, v0
	s_add_i32 m0, s19, 0x10000
	v_lshl_add_u32 v134, v3, 12, v0
	global_load_lds_dwordx4 v132, s[24:25]
	s_add_i32 m0, s19, 0x12000
	s_add_u32 s10, s24, 0x8000
	global_load_lds_dwordx4 v128, s[24:25]
	s_addc_u32 s11, s25, 0
	s_add_i32 m0, s19, 0x14000
	v_mov_b32_e32 v137, 0
	global_load_lds_dwordx4 v132, s[10:11]
	s_add_i32 m0, s19, 0x16000
	s_add_u32 s22, s58, s6
	s_addc_u32 s23, s59, s7
	s_add_i32 s37, s19, 0x2000
	global_load_lds_dwordx4 v128, s[10:11]
	s_mov_b32 m0, s19
	s_add_u32 s6, s22, 0x80000
	global_load_lds_dwordx4 v134, s[22:23]
	s_mov_b32 m0, s37
	s_addc_u32 s7, s23, 0
	s_add_i32 s38, s19, 0x4000
	global_load_lds_dwordx4 v130, s[22:23]
	s_mov_b32 m0, s38
	s_add_i32 s39, s19, 0x6000
	global_load_lds_dwordx4 v134, s[6:7]
	s_mov_b32 m0, s39
	v_mov_b32_e32 v133, v137
	global_load_lds_dwordx4 v130, s[6:7]
	v_mov_b32_e32 v129, v137
	v_mov_b32_e32 v135, v137
	v_mov_b32_e32 v131, v137
	s_cmp_eq_u32 s3, 1
	s_mov_b32 s5, 0
	v_lshl_add_u64 v[6:7], s[24:25], 0, v[132:133]
	v_lshl_add_u64 v[4:5], s[24:25], 0, v[128:129]
	v_lshl_add_u64 v[0:1], s[22:23], 0, v[134:135]
	s_cselect_b64 s[6:7], -1, 0
	s_cmp_lg_u32 s3, 1
	v_lshl_add_u64 v[2:3], s[22:23], 0, v[130:131]
	s_cbranch_scc1 .LBB0_539
	s_barrier

.LBB0_552:
	v_mov_b32_e32 v0, v188
	s_nop 0
	v_readfirstlane_b32 s2, v0
	s_ashr_i32 s2, s2, 6
	s_add_i32 s4, s2, s31
	s_cmpk_gt_i32 s4, 0x3ff
	s_cbranch_scc1 .Llr_done
	v_and_b32_e32 v1, 15, v0
	v_bfe_u32 v0, v0, 4, 2
	v_lshlrev_b32_e32 v4, 2, v1
	v_mov_b32_e32 v5, 0
	v_lshl_add_u64 v[6:7], s[0:1], 0, v[4:5]
	v_lshlrev_b32_e32 v4, 4, v0
	s_lshl_b32 s3, s30, 7
	s_lshl_b32 s2, s2, 4
	v_lshl_add_u64 v[8:9], s[50:51], 0, v[4:5]
	s_add_i32 s3, s3, s2
	v_lshl_or_b32 v4, v1, 12, v4
	v_lshlrev_b32_e32 v16, 2, v0
	v_or_b32_e32 v10, s3, v1
	s_lshl_b32 s5, s68, 7
	v_lshl_add_u64 v[12:13], s[50:51], 0, v[4:5]

.LBB0_534:
	v_lshl_add_u64 v[18:19], v[14:15], 0, s[2:3]
	v_add_co_u32_e32 v54, vcc, 0x3800000, v18
	v_lshl_add_u64 v[20:21], v[12:13], 0, s[2:3]
	s_nop 0
	v_addc_co_u32_e32 v55, vcc, 0, v19, vcc
	v_add_co_u32_e32 v56, vcc, 0x200000, v20
	s_add_u32 s2, s2, 0x200
	s_nop 0
	v_addc_co_u32_e32 v57, vcc, 0, v21, vcc
	global_load_dwordx4 v[18:21], v[54:55], off
	global_load_dwordx4 v[22:25], v[54:55], off offset:64
	global_load_dwordx4 v[26:29], v[54:55], off offset:128
	global_load_dwordx4 v[30:33], v[54:55], off offset:192
	global_load_dwordx4 v[34:37], v[54:55], off offset:256
	global_load_dwordx4 v[38:41], v[54:55], off offset:320
	global_load_dwordx4 v[42:45], v[54:55], off offset:384
	global_load_dwordx4 v[46:49], v[56:57], off
	global_load_dwordx4 v[50:53], v[56:57], off offset:64
	s_addc_u32 s3, s3, 0
	s_cmpk_eq_i32 s2, 0x1000
	s_waitcnt vmcnt(1)
	v_mfma_f32_16x16x32_bf16 v[0:3], v[18:21], v[46:49], v[0:3]
	global_load_dwordx4 v[18:21], v[56:57], off offset:128
	s_waitcnt vmcnt(1)
	v_mfma_f32_16x16x32_bf16 v[0:3], v[22:25], v[50:53], v[0:3]
	global_load_dwordx4 v[22:25], v[56:57], off offset:192
	s_waitcnt vmcnt(1)
	v_mfma_f32_16x16x32_bf16 v[0:3], v[26:29], v[18:21], v[0:3]
	global_load_dwordx4 v[18:21], v[56:57], off offset:256
	s_waitcnt vmcnt(1)
	v_mfma_f32_16x16x32_bf16 v[0:3], v[30:33], v[22:25], v[0:3]
	global_load_dwordx4 v[22:25], v[56:57], off offset:320
	global_load_dwordx4 v[26:29], v[54:55], off offset:448
	s_waitcnt vmcnt(2)
	v_mfma_f32_16x16x32_bf16 v[0:3], v[34:37], v[18:21], v[0:3]
	global_load_dwordx4 v[18:21], v[56:57], off offset:384
	s_waitcnt vmcnt(2)
	v_mfma_f32_16x16x32_bf16 v[0:3], v[38:41], v[22:25], v[0:3]
	global_load_dwordx4 v[22:25], v[56:57], off offset:448
	s_waitcnt vmcnt(1)
	v_mfma_f32_16x16x32_bf16 v[0:3], v[42:45], v[18:21], v[0:3]
	s_waitcnt vmcnt(0)
	v_mfma_f32_16x16x32_bf16 v[0:3], v[26:29], v[22:25], v[0:3]
	s_cbranch_scc0 .LBB0_534
	v_lshl_or_b32 v14, s4, 4, v16
	v_ashrrev_i32_e32 v15, 31, v14
	v_lshlrev_b64 v[18:19], 6, v[14:15]
	v_lshl_add_u64 v[18:19], v[6:7], 0, v[18:19]
	s_nop 2
	global_store_dword v[18:19], v0, off
	v_or_b32_e32 v18, 1, v14
	v_ashrrev_i32_e32 v19, 31, v18
	v_lshlrev_b64 v[18:19], 6, v[18:19]
	v_lshl_add_u64 v[18:19], v[6:7], 0, v[18:19]
	v_or_b32_e32 v0, 2, v14
	global_store_dword v[18:19], v1, off
	v_ashrrev_i32_e32 v1, 31, v0
	v_lshlrev_b64 v[0:1], 6, v[0:1]
	v_lshl_add_u64 v[0:1], v[6:7], 0, v[0:1]
	global_store_dword v[0:1], v2, off
	v_or_b32_e32 v0, 3, v14
	v_ashrrev_i32_e32 v1, 31, v0
	v_lshlrev_b64 v[0:1], 6, v[0:1]
	s_add_i32 s4, s4, s34
	v_lshl_add_u64 v[0:1], v[6:7], 0, v[0:1]
	s_cmpk_gt_i32 s4, 0x3ff
	v_add_u32_e32 v10, s5, v10
	global_store_dword v[0:1], v3, off
	s_cbranch_scc0 .LBB0_533
.Llr_done:
	s_waitcnt vmcnt(0)
	s_waitcnt vmcnt(0)
	s_barrier
	s_and_saveexec_b64 s[2:3], s[28:29]
	s_cbranch_execz .LBB0_604
	s_add_i32 s4, 0, 0x24800
	v_mov_b32_e32 v0, s4
	s_waitcnt vmcnt(0) expcnt(0) lgkmcnt(0)
	ds_read_b32 v2, v0
	s_add_i32 s4, 0, 0x24804
	v_mov_b32_e32 v0, s4
	ds_read_b32 v0, v0
	s_waitcnt lgkmcnt(1)
	v_cmp_ne_u32_e32 vcc, 0, v2
	s_cbranch_vccnz .LBB0_568
	v_readlane_b32 s4, v253, 0
	s_mul_i32 s18, s69, s4
	s_add_u32 s4, s50, 0x1000
	s_addc_u32 s5, s51, 0
	s_add_u32 s6, s50, 0x1100
	s_addc_u32 s7, s51, 0
	s_add_u32 s8, s50, 0x1200
	s_addc_u32 s9, s51, 0
	s_add_u32 s10, s50, 0x1300
	s_mul_i32 s18, s18, s68
	s_addc_u32 s11, s51, 0
	s_mov_b32 s19, 1
	v_mov_b32_e32 v16, 0
	s_branch .LBB0_556

.LBB0_692:
	v_mov_b32_e32 v2, v1
	v_mov_b32_e32 v3, v1
	v_mov_b32_e32 v94, v1
	v_mov_b32_e32 v95, v1
	v_lshl_add_u64 v[144:145], v[0:1], 1, s[56:57]
	s_lshl_b32 s10, s13, 10
	s_lshl_b32 s11, s14, 6
	v_mov_b32_e32 v0, v1
	v_mov_b32_e32 v92, v1
	v_mov_b32_e32 v93, v1
	v_mov_b64_e32 v[130:131], v[94:95]
	v_mov_b64_e32 v[102:103], v[94:95]
	v_mov_b64_e32 v[134:135], v[94:95]
	v_mov_b64_e32 v[106:107], v[94:95]
	v_mov_b64_e32 v[118:119], v[94:95]
	v_mov_b64_e32 v[114:115], v[94:95]
	v_mov_b64_e32 v[110:111], v[94:95]
	v_mov_b64_e32 v[78:79], v[2:3]
	s_add_i32 s10, s10, s35
	v_lshl_add_u32 v149, s14, 7, v179
	v_lshl_add_u32 v150, s14, 8, v178
	s_mov_b32 s38, 0
	s_lshl_b32 s11, s11, 2
	v_mov_b64_e32 v[128:129], v[92:93]
	v_mov_b64_e32 v[100:101], v[92:93]
	v_mov_b64_e32 v[132:133], v[92:93]
	v_mov_b64_e32 v[104:105], v[92:93]
	v_mov_b64_e32 v[116:117], v[92:93]
	v_mov_b64_e32 v[112:113], v[92:93]
	v_mov_b64_e32 v[108:109], v[92:93]
	v_mov_b64_e32 v[76:77], v[0:1]
	v_and_b32_e32 v201, 63, v170
	v_bfe_u32 v202, v201, 3, 2
	s_bfe_u32 s98, s27, 0x40003
	s_lshl_b32 s98, s98, 2
	v_add_u32_e32 v202, s98, v202
	v_mul_u32_u24_e32 v202, 0x6080, v202
	v_and_b32_e32 v203, 3, v201
	v_lshlrev_b32_e32 v203, 7, v203
	v_bfe_u32 v204, v201, 2, 1
	v_lshlrev_b32_e32 v204, 12, v204
	s_lshl_b32 s99, s35, 9
	v_add3_u32 v201, v202, v203, v204
	v_add_u32_e32 v201, s99, v201
	s_branch .LBB0_694

.LBB0_694:
	s_waitcnt lgkmcnt(0)
	s_barrier
.LBB0_696:
	s_and_b32 s41, s38, 1
	s_lshl_b32 s40, s41, 10
	s_mul_i32 s39, s41, 0x1200
	s_add_i32 s40, s40, 0
	v_add_u32_e32 v0, s39, v178
	s_add_i32 s39, s11, s40
	v_add_u32_e32 v3, v0, v180
	v_lshl_add_u32 v0, v177, 2, s39
	ds_read_b128 v[152:155], v0 offset:43008
	ds_read_b128 v[156:159], v3 offset:33792
	ds_read_b128 v[160:163], v3 offset:33856
	ds_read_b128 v[164:167], v3 offset:36096
	ds_read_b128 v[196:199], v3 offset:36160
	s_xor_b32 s42, s41, 1
	s_waitcnt lgkmcnt(4)
	v_pk_mul_f32 v[110:111], v[110:111], v[154:155]
	v_pk_mul_f32 v[108:109], v[108:109], v[152:153]
	v_pk_mul_f32 v[114:115], v[114:115], v[154:155]
	v_pk_mul_f32 v[112:113], v[112:113], v[152:153]
	s_waitcnt vmcnt(15) lgkmcnt(3)
	v_mfma_f32_16x16x32_bf16 v[108:111], v[48:51], v[156:159], v[108:111]
	s_mul_i32 s39, s42, 0x4200
	v_add_u32_e32 v2, s39, v149
	v_add_u32_e32 v2, v2, v181
	s_waitcnt lgkmcnt(1)
	v_mfma_f32_16x16x32_bf16 v[48:51], v[48:51], v[164:167], v[112:115]
	s_and_b64 vcc, exec, s[6:7]
	s_lshl_b32 s39, s42, 10
	s_waitcnt vmcnt(14)
	v_mfma_f32_16x16x32_bf16 v[108:111], v[52:55], v[160:163], v[108:111]
	s_waitcnt lgkmcnt(0)
	v_mfma_f32_16x16x32_bf16 v[112:115], v[52:55], v[196:199], v[48:51]
	s_nop 5
	v_cvt_pk_bf16_f32 v168, v108, v109
	v_cvt_pk_bf16_f32 v169, v110, v111
	v_cvt_pk_bf16_f32 v48, v112, v113
	v_cvt_pk_bf16_f32 v49, v114, v115
	ds_write_b64 v2, v[168:169]
	ds_write_b64 v2, v[48:49] offset:8448
	ds_read_b128 v[48:51], v0 offset:43072
	s_waitcnt lgkmcnt(0)
	v_pk_mul_f32 v[54:55], v[118:119], v[50:51]
	v_pk_mul_f32 v[52:53], v[116:117], v[48:49]
	v_pk_mul_f32 v[50:51], v[106:107], v[50:51]
	v_pk_mul_f32 v[48:49], v[104:105], v[48:49]
	s_waitcnt vmcnt(13)
	v_mfma_f32_16x16x32_bf16 v[52:55], v[40:43], v[156:159], v[52:55]
	v_mfma_f32_16x16x32_bf16 v[40:43], v[40:43], v[164:167], v[48:51]
	s_waitcnt vmcnt(12)
	v_mfma_f32_16x16x32_bf16 v[116:119], v[44:47], v[160:163], v[52:55]
	v_mfma_f32_16x16x32_bf16 v[104:107], v[44:47], v[196:199], v[40:43]
	s_nop 6
	v_cvt_pk_bf16_f32 v48, v116, v117
	v_cvt_pk_bf16_f32 v49, v118, v119
	v_cvt_pk_bf16_f32 v40, v104, v105
	v_cvt_pk_bf16_f32 v41, v106, v107
	ds_write_b64 v2, v[48:49] offset:32
	ds_write_b64 v2, v[40:41] offset:8480
	ds_read_b128 v[40:43], v0 offset:43136
	s_waitcnt lgkmcnt(0)
	v_pk_mul_f32 v[46:47], v[134:135], v[42:43]
	v_pk_mul_f32 v[44:45], v[132:133], v[40:41]
	v_pk_mul_f32 v[42:43], v[102:103], v[42:43]
	v_pk_mul_f32 v[40:41], v[100:101], v[40:41]
	s_waitcnt vmcnt(11)
	v_mfma_f32_16x16x32_bf16 v[44:47], v[28:31], v[156:159], v[44:47]
	v_mfma_f32_16x16x32_bf16 v[28:31], v[28:31], v[164:167], v[40:43]
	s_waitcnt vmcnt(10)
	v_mfma_f32_16x16x32_bf16 v[132:135], v[32:35], v[160:163], v[44:47]
	v_mfma_f32_16x16x32_bf16 v[100:103], v[32:35], v[196:199], v[28:31]
	s_nop 6
	v_cvt_pk_bf16_f32 v40, v132, v133
	v_cvt_pk_bf16_f32 v41, v134, v135
	v_cvt_pk_bf16_f32 v28, v100, v101
	v_cvt_pk_bf16_f32 v29, v102, v103
	ds_write_b64 v2, v[40:41] offset:64
	ds_write_b64 v2, v[28:29] offset:8512
	ds_read_b128 v[28:31], v0 offset:43200
	s_waitcnt lgkmcnt(0)
	v_pk_mul_f32 v[34:35], v[130:131], v[30:31]
	v_pk_mul_f32 v[32:33], v[128:129], v[28:29]
	v_pk_mul_f32 v[30:31], v[94:95], v[30:31]
	v_pk_mul_f32 v[28:29], v[92:93], v[28:29]
	s_waitcnt vmcnt(9)
	v_mfma_f32_16x16x32_bf16 v[32:35], v[16:19], v[156:159], v[32:35]
	v_mfma_f32_16x16x32_bf16 v[16:19], v[16:19], v[164:167], v[28:31]
	s_waitcnt vmcnt(8)
	v_mfma_f32_16x16x32_bf16 v[128:131], v[20:23], v[160:163], v[32:35]
	v_mfma_f32_16x16x32_bf16 v[92:95], v[20:23], v[196:199], v[16:19]
	s_nop 6
	v_cvt_pk_bf16_f32 v28, v128, v129
	v_cvt_pk_bf16_f32 v29, v130, v131
	v_cvt_pk_bf16_f32 v16, v92, v93
	v_cvt_pk_bf16_f32 v17, v94, v95
	ds_write_b64 v2, v[28:29] offset:96
	ds_write_b64 v2, v[16:17] offset:8544
	s_min_u32 s98, s38, 0x7d
	s_add_i32 s98, s98, 2
	s_lshl_b32 s99, s98, 6
	s_add_i32 s99, s99, s37
	s_mul_hi_i32 s101, s99, 0x6080
	s_mul_i32 s100, s99, 0x6080
	v_lshl_add_u64 v[140:141], v[144:145], 0, s[100:101]
	s_mov_b32 s101, 0
	s_mov_b32 s100, 0xc000
	v_lshl_add_u64 v[136:137], v[140:141], 0, s[100:101]
	s_mov_b32 s100, 0x18000
	v_lshl_add_u64 v[124:125], v[140:141], 0, s[100:101]
	s_mov_b32 s100, 0x24000
	v_lshl_add_u64 v[120:121], v[140:141], 0, s[100:101]
	s_mov_b32 s100, 0x30000
	v_lshl_add_u64 v[96:97], v[140:141], 0, s[100:101]
	s_mov_b32 s100, 0x3c000
	v_lshl_add_u64 v[88:89], v[140:141], 0, s[100:101]
	s_mov_b32 s100, 0x48000
	v_lshl_add_u64 v[84:85], v[140:141], 0, s[100:101]
	s_mov_b32 s100, 0x54000
	v_lshl_add_u64 v[80:81], v[140:141], 0, s[100:101]
	global_load_dwordx4 v[140:143], v[140:141], off
	global_load_dwordx4 v[136:139], v[136:137], off offset:256
	global_load_dwordx4 v[124:127], v[124:125], off offset:512
	global_load_dwordx4 v[120:123], v[120:121], off offset:768
	global_load_dwordx4 v[96:99], v[96:97], off offset:1024
	global_load_dwordx4 v[88:91], v[88:89], off offset:1280
	global_load_dwordx4 v[84:87], v[84:85], off offset:1536
	global_load_dwordx4 v[80:83], v[80:81], off offset:1792
	s_cmp_lg_u64 s[6:7], 0
	s_cbranch_scc1 .Lst_nodec_p9a
	s_add_i32 s99, s98, 2
	s_min_u32 s99, s99, 0x7f
	s_lshl_b32 s99, s99, 6
	s_add_i32 s99, s99, s37
	s_mul_hi_u32 s101, s99, 0x6080
	s_mul_i32 s100, s99, 0x6080
	s_add_u32 s100, s100, s56
	s_addc_u32 s101, s101, s57
	global_load_dword v202, v201, s[100:101]
	s_lshl_b32 s98, s98, 3
	s_add_i32 s100, s98, s10
	s_ashr_i32 s101, s100, 31
	s_lshl_b64 s[100:101], s[100:101], 10
	v_lshl_add_u64 v[76:77], v[146:147], 0, s[100:101]
	global_load_dwordx4 v[76:79], v[76:77], off
.Lst_nodec_p9a:
	s_cbranch_vccnz .LBB0_698
	v_add_u32_e32 v16, s39, v176
	s_waitcnt vmcnt(10)
	ds_write_b128 v16, v[60:63] offset:43008

.LBB0_700:
	v_add_u32_e32 v151, s39, v150
	s_mulk_i32 s42, 0x1200
	ds_read_b128 v[152:155], v151 offset:43008
	v_add3_u32 v168, v178, s42, v180
	ds_read_b128 v[156:159], v168 offset:33792
	ds_read_b128 v[160:163], v168 offset:33856
	ds_read_b128 v[164:167], v168 offset:36096
	ds_read_b128 v[196:199], v168 offset:36160
	s_mulk_i32 s41, 0x4200
	s_waitcnt lgkmcnt(4)
	v_pk_mul_f32 v[110:111], v[110:111], v[154:155]
	v_pk_mul_f32 v[108:109], v[108:109], v[152:153]
	v_pk_mul_f32 v[114:115], v[114:115], v[154:155]
	v_pk_mul_f32 v[112:113], v[112:113], v[152:153]
	s_waitcnt vmcnt(15) lgkmcnt(3)
	v_mfma_f32_16x16x32_bf16 v[108:111], v[8:11], v[156:159], v[108:111]
	v_add3_u32 v168, v149, s41, v181
	s_and_b64 vcc, exec, s[6:7]
	s_waitcnt lgkmcnt(1)
	v_mfma_f32_16x16x32_bf16 v[112:115], v[8:11], v[164:167], v[112:115]
	s_waitcnt vmcnt(14)
	v_mfma_f32_16x16x32_bf16 v[108:111], v[12:15], v[160:163], v[108:111]
	s_waitcnt lgkmcnt(0)
	v_mfma_f32_16x16x32_bf16 v[112:115], v[12:15], v[196:199], v[112:115]
	s_nop 5
	v_cvt_pk_bf16_f32 v152, v108, v109
	v_cvt_pk_bf16_f32 v153, v110, v111
	ds_write_b64 v168, v[152:153]
	v_cvt_pk_bf16_f32 v152, v112, v113
	v_cvt_pk_bf16_f32 v153, v114, v115
	ds_write_b64 v168, v[152:153] offset:8448
	ds_read_b128 v[152:155], v151 offset:43072
	s_waitcnt lgkmcnt(0)
	v_pk_mul_f32 v[118:119], v[118:119], v[154:155]
	v_pk_mul_f32 v[116:117], v[116:117], v[152:153]
	v_pk_mul_f32 v[106:107], v[106:107], v[154:155]
	v_pk_mul_f32 v[104:105], v[104:105], v[152:153]
	s_waitcnt vmcnt(13)
	v_mfma_f32_16x16x32_bf16 v[116:119], v[24:27], v[156:159], v[116:119]
	v_mfma_f32_16x16x32_bf16 v[104:107], v[24:27], v[164:167], v[104:107]
	s_waitcnt vmcnt(12)
	v_mfma_f32_16x16x32_bf16 v[116:119], v[36:39], v[160:163], v[116:119]
	v_mfma_f32_16x16x32_bf16 v[104:107], v[36:39], v[196:199], v[104:107]
	s_nop 6
	v_cvt_pk_bf16_f32 v152, v116, v117
	v_cvt_pk_bf16_f32 v153, v118, v119
	ds_write_b64 v168, v[152:153] offset:32
	v_cvt_pk_bf16_f32 v152, v104, v105
	v_cvt_pk_bf16_f32 v153, v106, v107
	ds_write_b64 v168, v[152:153] offset:8480
	ds_read_b128 v[152:155], v151 offset:43136
	s_waitcnt lgkmcnt(0)
	v_pk_mul_f32 v[134:135], v[134:135], v[154:155]
	v_pk_mul_f32 v[132:133], v[132:133], v[152:153]
	v_pk_mul_f32 v[102:103], v[102:103], v[154:155]
	v_pk_mul_f32 v[100:101], v[100:101], v[152:153]
	s_waitcnt vmcnt(11)
	v_mfma_f32_16x16x32_bf16 v[132:135], v[56:59], v[156:159], v[132:135]
	v_mfma_f32_16x16x32_bf16 v[100:103], v[56:59], v[164:167], v[100:103]
	s_waitcnt vmcnt(10)
	v_mfma_f32_16x16x32_bf16 v[132:135], v[64:67], v[160:163], v[132:135]
	v_mfma_f32_16x16x32_bf16 v[100:103], v[64:67], v[196:199], v[100:103]
	s_nop 6
	v_cvt_pk_bf16_f32 v152, v132, v133
	v_cvt_pk_bf16_f32 v153, v134, v135
	ds_write_b64 v168, v[152:153] offset:64
	v_cvt_pk_bf16_f32 v152, v100, v101
	v_cvt_pk_bf16_f32 v153, v102, v103
	ds_write_b64 v168, v[152:153] offset:8512
	ds_read_b128 v[152:155], v151 offset:43200
	s_waitcnt lgkmcnt(0)
	v_pk_mul_f32 v[130:131], v[130:131], v[154:155]
	v_pk_mul_f32 v[128:129], v[128:129], v[152:153]
	v_pk_mul_f32 v[94:95], v[94:95], v[154:155]
	v_pk_mul_f32 v[92:93], v[92:93], v[152:153]
	s_waitcnt vmcnt(9)
	v_mfma_f32_16x16x32_bf16 v[128:131], v[68:71], v[156:159], v[128:131]
	v_mfma_f32_16x16x32_bf16 v[92:95], v[68:71], v[164:167], v[92:95]
	s_waitcnt vmcnt(8)
	v_mfma_f32_16x16x32_bf16 v[128:131], v[72:75], v[160:163], v[128:131]
	v_mfma_f32_16x16x32_bf16 v[92:95], v[72:75], v[196:199], v[92:95]
	s_nop 6
	v_cvt_pk_bf16_f32 v152, v128, v129
	v_cvt_pk_bf16_f32 v153, v130, v131
	ds_write_b64 v168, v[152:153] offset:96
	v_cvt_pk_bf16_f32 v152, v92, v93
	v_cvt_pk_bf16_f32 v153, v94, v95
	ds_write_b64 v168, v[152:153] offset:8544
	s_min_u32 s98, s38, 0x7c
	s_add_i32 s98, s98, 3
	s_lshl_b32 s99, s98, 6
	s_add_i32 s99, s99, s37
	s_mul_hi_i32 s101, s99, 0x6080
	s_mul_i32 s100, s99, 0x6080
	v_lshl_add_u64 v[48:49], v[144:145], 0, s[100:101]
	s_mov_b32 s101, 0
	s_mov_b32 s100, 0xc000
	v_lshl_add_u64 v[52:53], v[48:49], 0, s[100:101]
	s_mov_b32 s100, 0x18000
	v_lshl_add_u64 v[40:41], v[48:49], 0, s[100:101]
	s_mov_b32 s100, 0x24000
	v_lshl_add_u64 v[44:45], v[48:49], 0, s[100:101]
	s_mov_b32 s100, 0x30000
	v_lshl_add_u64 v[28:29], v[48:49], 0, s[100:101]
	s_mov_b32 s100, 0x3c000
	v_lshl_add_u64 v[32:33], v[48:49], 0, s[100:101]
	s_mov_b32 s100, 0x48000
	v_lshl_add_u64 v[16:17], v[48:49], 0, s[100:101]
	s_mov_b32 s100, 0x54000
	v_lshl_add_u64 v[20:21], v[48:49], 0, s[100:101]
	global_load_dwordx4 v[48:51], v[48:49], off
	global_load_dwordx4 v[52:55], v[52:53], off offset:256
	global_load_dwordx4 v[40:43], v[40:41], off offset:512
	global_load_dwordx4 v[44:47], v[44:45], off offset:768
	global_load_dwordx4 v[28:31], v[28:29], off offset:1024
	global_load_dwordx4 v[32:35], v[32:33], off offset:1280
	global_load_dwordx4 v[16:19], v[16:17], off offset:1536
	global_load_dwordx4 v[20:23], v[20:21], off offset:1792
	s_cmp_lg_u64 s[6:7], 0
	s_cbranch_scc1 .Lst_nodec_p9b
	s_add_i32 s99, s98, 2
	s_min_u32 s99, s99, 0x7f
	s_lshl_b32 s99, s99, 6
	s_add_i32 s99, s99, s37
	s_mul_hi_u32 s101, s99, 0x6080
	s_mul_i32 s100, s99, 0x6080
	s_add_u32 s100, s100, s56
	s_addc_u32 s101, s101, s57
	global_load_dword v202, v201, s[100:101]
	s_lshl_b32 s98, s98, 3
	s_add_i32 s100, s98, s10
	s_ashr_i32 s101, s100, 31
	s_lshl_b64 s[100:101], s[100:101], 10
	v_lshl_add_u64 v[4:5], v[146:147], 0, s[100:101]
	global_load_dwordx4 v[4:7], v[4:5], off
.Lst_nodec_p9b:
	s_cbranch_vccnz .LBB0_702
	v_lshl_add_u32 v151, v174, 2, s40
	s_waitcnt vmcnt(10)
	ds_write_b128 v151, v[76:79] offset:43008
.LBB0_702:
	s_cmpk_gt_u32 s38, 0x7d
	s_cbranch_scc1 .LBB0_693
	s_waitcnt lgkmcnt(0)
	s_barrier
.LBB0_705:
	ds_read_b128 v[152:155], v0 offset:43008
	ds_read_b128 v[156:159], v3 offset:33792
	ds_read_b128 v[160:163], v3 offset:33856
	ds_read_b128 v[164:167], v3 offset:36096
	s_and_b64 vcc, exec, s[6:7]
	s_waitcnt lgkmcnt(3)
	v_pk_mul_f32 v[110:111], v[110:111], v[154:155]
	v_pk_mul_f32 v[108:109], v[108:109], v[152:153]
	v_pk_mul_f32 v[114:115], v[114:115], v[154:155]
	v_pk_mul_f32 v[112:113], v[112:113], v[152:153]
	s_waitcnt vmcnt(15) lgkmcnt(2)
	v_mfma_f32_16x16x32_bf16 v[108:111], v[140:143], v[156:159], v[108:111]
	s_waitcnt lgkmcnt(0)
	v_mfma_f32_16x16x32_bf16 v[112:115], v[140:143], v[164:167], v[112:115]
	ds_read_b128 v[140:143], v3 offset:36160
	s_waitcnt vmcnt(14)
	v_mfma_f32_16x16x32_bf16 v[108:111], v[136:139], v[160:163], v[108:111]
	s_waitcnt lgkmcnt(0)
	v_mfma_f32_16x16x32_bf16 v[112:115], v[136:139], v[140:143], v[112:115]
	s_nop 5
	v_cvt_pk_bf16_f32 v152, v108, v109
	v_cvt_pk_bf16_f32 v153, v110, v111
	v_cvt_pk_bf16_f32 v136, v112, v113
	v_cvt_pk_bf16_f32 v137, v114, v115
	ds_write_b64 v2, v[152:153]
	ds_write_b64 v2, v[136:137] offset:8448
	ds_read_b128 v[136:139], v0 offset:43072
	s_waitcnt lgkmcnt(0)
	v_pk_mul_f32 v[118:119], v[118:119], v[138:139]
	v_pk_mul_f32 v[116:117], v[116:117], v[136:137]
	v_pk_mul_f32 v[106:107], v[106:107], v[138:139]
	v_pk_mul_f32 v[104:105], v[104:105], v[136:137]
	s_waitcnt vmcnt(13)
	v_mfma_f32_16x16x32_bf16 v[116:119], v[124:127], v[156:159], v[116:119]
	v_mfma_f32_16x16x32_bf16 v[104:107], v[124:127], v[164:167], v[104:107]
	s_waitcnt vmcnt(12)
	v_mfma_f32_16x16x32_bf16 v[116:119], v[120:123], v[160:163], v[116:119]
	v_mfma_f32_16x16x32_bf16 v[104:107], v[120:123], v[140:143], v[104:107]
	s_nop 6
	v_cvt_pk_bf16_f32 v124, v116, v117
	v_cvt_pk_bf16_f32 v125, v118, v119
	v_cvt_pk_bf16_f32 v120, v104, v105
	v_cvt_pk_bf16_f32 v121, v106, v107
	ds_write_b64 v2, v[124:125] offset:32
	ds_write_b64 v2, v[120:121] offset:8480
	ds_read_b128 v[120:123], v0 offset:43136
	s_waitcnt lgkmcnt(0)
	v_pk_mul_f32 v[126:127], v[134:135], v[122:123]
	v_pk_mul_f32 v[124:125], v[132:133], v[120:121]
	v_pk_mul_f32 v[102:103], v[102:103], v[122:123]
	v_pk_mul_f32 v[100:101], v[100:101], v[120:121]
	s_waitcnt vmcnt(11)
	v_mfma_f32_16x16x32_bf16 v[124:127], v[96:99], v[156:159], v[124:127]
	v_mfma_f32_16x16x32_bf16 v[96:99], v[96:99], v[164:167], v[100:103]
	s_waitcnt vmcnt(10)
	v_mfma_f32_16x16x32_bf16 v[132:135], v[88:91], v[160:163], v[124:127]
	v_mfma_f32_16x16x32_bf16 v[100:103], v[88:91], v[140:143], v[96:99]
	s_nop 6
	v_cvt_pk_bf16_f32 v120, v132, v133
	v_cvt_pk_bf16_f32 v121, v134, v135
	v_cvt_pk_bf16_f32 v88, v100, v101
	v_cvt_pk_bf16_f32 v89, v102, v103
	ds_write_b64 v2, v[120:121] offset:64
	ds_write_b64 v2, v[88:89] offset:8512
	ds_read_b128 v[88:91], v0 offset:43200
	s_waitcnt lgkmcnt(0)
	v_pk_mul_f32 v[98:99], v[130:131], v[90:91]
	v_pk_mul_f32 v[96:97], v[128:129], v[88:89]
	v_pk_mul_f32 v[90:91], v[94:95], v[90:91]
	v_pk_mul_f32 v[88:89], v[92:93], v[88:89]
	s_waitcnt vmcnt(9)
	v_mfma_f32_16x16x32_bf16 v[96:99], v[84:87], v[156:159], v[96:99]
	v_mfma_f32_16x16x32_bf16 v[84:87], v[84:87], v[164:167], v[88:91]
	s_waitcnt vmcnt(8)
	v_mfma_f32_16x16x32_bf16 v[128:131], v[80:83], v[160:163], v[96:99]
	v_mfma_f32_16x16x32_bf16 v[92:95], v[80:83], v[140:143], v[84:87]
	s_nop 6
	v_cvt_pk_bf16_f32 v88, v128, v129
	v_cvt_pk_bf16_f32 v89, v130, v131
	v_cvt_pk_bf16_f32 v80, v92, v93
	v_cvt_pk_bf16_f32 v81, v94, v95
	ds_write_b64 v2, v[88:89] offset:96
	ds_write_b64 v2, v[80:81] offset:8544
	s_min_u32 s98, s38, 0x7b
	s_add_i32 s98, s98, 4
	s_lshl_b32 s99, s98, 6
	s_add_i32 s99, s99, s37
	s_mul_hi_i32 s101, s99, 0x6080
	s_mul_i32 s100, s99, 0x6080
	v_lshl_add_u64 v[8:9], v[144:145], 0, s[100:101]
	s_mov_b32 s101, 0
	s_mov_b32 s100, 0xc000
	v_lshl_add_u64 v[12:13], v[8:9], 0, s[100:101]
	s_mov_b32 s100, 0x18000
	v_lshl_add_u64 v[24:25], v[8:9], 0, s[100:101]
	s_mov_b32 s100, 0x24000
	v_lshl_add_u64 v[36:37], v[8:9], 0, s[100:101]
	s_mov_b32 s100, 0x30000
	v_lshl_add_u64 v[56:57], v[8:9], 0, s[100:101]
	s_mov_b32 s100, 0x3c000
	v_lshl_add_u64 v[64:65], v[8:9], 0, s[100:101]
	s_mov_b32 s100, 0x48000
	v_lshl_add_u64 v[68:69], v[8:9], 0, s[100:101]
	s_mov_b32 s100, 0x54000
	v_lshl_add_u64 v[72:73], v[8:9], 0, s[100:101]
	global_load_dwordx4 v[8:11], v[8:9], off
	global_load_dwordx4 v[12:15], v[12:13], off offset:256
	global_load_dwordx4 v[24:27], v[24:25], off offset:512
	global_load_dwordx4 v[36:39], v[36:37], off offset:768
	global_load_dwordx4 v[56:59], v[56:57], off offset:1024
	global_load_dwordx4 v[64:67], v[64:65], off offset:1280
	global_load_dwordx4 v[68:71], v[68:69], off offset:1536
	global_load_dwordx4 v[72:75], v[72:73], off offset:1792
	s_cmp_lg_u64 s[6:7], 0
	s_cbranch_scc1 .Lst_nodec_p9c
	s_add_i32 s99, s98, 2
	s_min_u32 s99, s99, 0x7f
	s_lshl_b32 s99, s99, 6
	s_add_i32 s99, s99, s37
	s_mul_hi_u32 s101, s99, 0x6080
	s_mul_i32 s100, s99, 0x6080
	s_add_u32 s100, s100, s56
	s_addc_u32 s101, s101, s57
	global_load_dword v202, v201, s[100:101]
	s_lshl_b32 s98, s98, 3
	s_add_i32 s100, s98, s10
	s_ashr_i32 s101, s100, 31
	s_lshl_b64 s[100:101], s[100:101], 10
	v_lshl_add_u64 v[60:61], v[146:147], 0, s[100:101]
	global_load_dwordx4 v[60:63], v[60:61], off
.Lst_nodec_p9c:
	s_cbranch_vccnz .LBB0_693
	v_add_u32_e32 v0, s39, v176
	s_waitcnt vmcnt(10)
	ds_write_b128 v0, v[4:7] offset:43008
	s_branch .LBB0_693

	.amdhsa_kernel _Z9trunk_fwd4Args
		.amdhsa_group_segment_fixed_size 0
		.amdhsa_private_segment_fixed_size 0
		.amdhsa_kernarg_size 392
		.amdhsa_user_sgpr_count 2
		.amdhsa_user_sgpr_dispatch_ptr 0
		.amdhsa_user_sgpr_queue_ptr 0
		.amdhsa_user_sgpr_kernarg_segment_ptr 1
		.amdhsa_user_sgpr_dispatch_id 0
		.amdhsa_user_sgpr_kernarg_preload_length 0
		.amdhsa_user_sgpr_kernarg_preload_offset 0
		.amdhsa_user_sgpr_private_segment_size 0
		.amdhsa_uses_dynamic_stack 0
		.amdhsa_enable_private_segment 0
		.amdhsa_system_sgpr_workgroup_id_x 1
		.amdhsa_system_sgpr_workgroup_id_y 0
		.amdhsa_system_sgpr_workgroup_id_z 0
		.amdhsa_system_sgpr_workgroup_info 0
		.amdhsa_system_vgpr_workitem_id 2
		.amdhsa_next_free_vgpr 254
		.amdhsa_next_free_sgpr 102
		.amdhsa_accum_offset 256
		.amdhsa_reserve_vcc 1
		.amdhsa_float_round_mode_32 0
		.amdhsa_float_round_mode_16_64 0
		.amdhsa_float_denorm_mode_32 3
		.amdhsa_float_denorm_mode_16_64 3
		.amdhsa_dx10_clamp 1
		.amdhsa_ieee_mode 1
		.amdhsa_fp16_overflow 0
		.amdhsa_tg_split 0
		.amdhsa_exception_fp_ieee_invalid_op 0
		.amdhsa_exception_fp_denorm_src 0
		.amdhsa_exception_fp_ieee_div_zero 0
		.amdhsa_exception_fp_ieee_overflow 0
		.amdhsa_exception_fp_ieee_underflow 0
		.amdhsa_exception_fp_ieee_inexact 0
		.amdhsa_exception_int_div_zero 0
	.end_amdhsa_kernel

amdhsa.kernels:
  - .agpr_count:     0
    .args:
      - .offset:         0
        .size:           136
        .value_kind:     by_value
      - .offset:         136
        .size:           4
        .value_kind:     hidden_block_count_x
      - .offset:         140
        .size:           4
        .value_kind:     hidden_block_count_y
      - .offset:         144
        .size:           4
        .value_kind:     hidden_block_count_z
      - .offset:         148
        .size:           2
        .value_kind:     hidden_group_size_x
      - .offset:         150
        .size:           2
        .value_kind:     hidden_group_size_y
      - .offset:         152
        .size:           2
        .value_kind:     hidden_group_size_z
      - .offset:         154
        .size:           2
        .value_kind:     hidden_remainder_x
      - .offset:         156
        .size:           2
        .value_kind:     hidden_remainder_y
      - .offset:         158
        .size:           2
        .value_kind:     hidden_remainder_z
      - .offset:         176
        .size:           8
        .value_kind:     hidden_global_offset_x
      - .offset:         184
        .size:           8
        .value_kind:     hidden_global_offset_y
      - .offset:         192
        .size:           8
        .value_kind:     hidden_global_offset_z
      - .offset:         200
        .size:           2
        .value_kind:     hidden_grid_dims
      - .offset:         224
        .size:           8
        .value_kind:     hidden_multigrid_sync_arg
      - .offset:         256
        .size:           4
        .value_kind:     hidden_dynamic_lds_size
    .group_segment_fixed_size: 0
    .kernarg_segment_align: 8
    .kernarg_segment_size: 392
    .language:       OpenCL C
    .language_version:
      - 2
      - 0
    .max_flat_workgroup_size: 512
    .name:           _Z9trunk_fwd4Args
    .private_segment_fixed_size: 0
    .sgpr_count:     108
    .sgpr_spill_count: 5
    .symbol:         _Z9trunk_fwd4Args.kd
    .uniform_work_group_size: 1
    .uses_dynamic_stack: false
    .vgpr_count:     254
    .vgpr_spill_count: 0
    .wavefront_size: 64
